# v21 plus MLA loop: absolute K/V/rotary pointers kept in registers, per-iteration address arithmetic removed (9 fewer instructions per iteration)
# speedup vs baseline: 1.0049x; 1.0049x over previous
; #define SLOAD(i, k0) do { st_[i].vs = *reinterpret_cast<const bf16x8*>(&Vh[(size_t)((k0) + sr) * LDK + sc]); \
;     st_[i].ks = *reinterpret_cast<const bf16x8*>(&Kh[(size_t)((k0) + sr) * LDK + sc]); \
;     if (DQ == 96) st_[i].kr = *reinterpret_cast<const bf16x8*>(&Kr[(size_t)((k0) + sr2) * 32 + sc2]); } while (0)
; #define SWRITE(b, i) do { *(bf16x8*)(V_lds + (b) * SHM_V + vst0) = st_[i].vs; *(bf16x8*)(K_lds + (b) * SHM_K + kst0) = st_[i].ks; \
;     if (DQ == 96) { if (tid < 256) *(bf16x8*)(K_lds + (b) * SHM_K + kst2) = st_[i].kr; } } while (0)
; #define SWAIT() do { if (DQ == 96) asm volatile("s_waitcnt vmcnt(3)" ::: "memory"); else asm volatile("s_waitcnt vmcnt(2)" ::: "memory"); } while (0)
; #define SLOAD(i, k0) do { st_[i].vs = *reinterpret_cast<const bf16x8*>(&Vh[(size_t)((k0) + sr) * LDK + sc]); \
;     st_[i].ks = *reinterpret_cast<const bf16x8*>(&Kh[(size_t)((k0) + sr) * LDK + sc]); \
;     if (DQ == 96) st_[i].kr = *reinterpret_cast<const bf16x8*>(&Kr[(size_t)((k0) + sr2) * 32 + sc2]); } while (0)
; #define SWRITE(b, i) do { *(bf16x8*)(V_lds + (b) * SHM_V + vst0) = st_[i].vs; *(bf16x8*)(K_lds + (b) * SHM_K + kst0) = st_[i].ks; \
;     if (DQ == 96) { if (tid < 256) *(bf16x8*)(K_lds + (b) * SHM_K + kst2) = st_[i].kr; } } while (0)
; #define SWAIT() do { if (DQ == 96) asm volatile("s_waitcnt vmcnt(3)" ::: "memory"); else asm volatile("s_waitcnt vmcnt(2)" ::: "memory"); } while (0)
; template <int DQ, bool WIN, int LDQ, int LDK> ...
;     ...
;     SLOAD(SE, KBASE(0)); SLOAD(SO, KBASE(1));
;     SWAIT(); SWRITE(0, SE); __syncthreads();
;     qkt<DQ>(pA0, pA1, K_lds, qr, zero16, r32, hi);
;     if (WIN) win_mask(pA0, pA1, qrow - KBASE(0), hi);
;     { const float pm = row_max32(pA0, pA1); m_ref = (pm > -1e37f) ? pm : 0.f;
; #pragma unroll
;       for (int r = 0; r < 16; ++r) { minit[r] = -m_ref; pA0[r] -= m_ref; pA1[r] -= m_ref; } }
.LBB0_1088:
	s_or_b64 exec, exec, s[16:17]
	v_and_b32_e32 v188, 31, v80
	s_movk_i32 s16, 0xd0
	v_mad_u32_u24 v0, v188, s16, 0
	v_add_u32_e32 v191, v0, v112
	s_waitcnt lgkmcnt(0)
	s_barrier
	ds_read_b128 v[0:3], v191 offset:16384
	ds_read_b128 v[52:55], v191 offset:16416
	s_waitcnt lgkmcnt(1)
	v_mfma_f32_32x32x16_bf16 v[16:31], v[0:3], v[134:137], 0
	ds_read_b128 v[0:3], v191 offset:23040
	ds_read_b128 v[56:59], v191 offset:23072
	v_lshl_or_b32 v50, v50, 1, v44
	v_mov_b32_e32 v51, v45
	v_lshl_add_u64 v[50:51], s[6:7], 0, v[50:51]
	s_mov_b64 s[16:17], 0x80000
	s_waitcnt lgkmcnt(1)
	v_mfma_f32_32x32x16_bf16 v[0:15], v[0:3], v[134:137], 0
	v_mfma_f32_32x32x16_bf16 v[16:31], v[52:55], v[130:133], v[16:31]
	s_waitcnt lgkmcnt(0)
	v_mfma_f32_32x32x16_bf16 v[0:15], v[56:59], v[130:133], v[0:15]
	ds_read_b128 v[52:55], v191 offset:16448
	ds_read_b128 v[56:59], v191 offset:16480
	s_waitcnt lgkmcnt(1)
	v_mfma_f32_32x32x16_bf16 v[16:31], v[52:55], v[126:129], v[16:31]
	ds_read_b128 v[52:55], v191 offset:23104
	ds_read_b128 v[60:63], v191 offset:23136
	s_waitcnt lgkmcnt(2)
	v_mfma_f32_32x32x16_bf16 v[16:31], v[56:59], v[122:125], v[16:31]
	v_lshl_add_u64 v[56:57], v[50:51], 0, s[16:17]
	v_add_co_u32_e32 v50, vcc, 0x80000, v50
	s_mov_b32 s16, 0xfcf0bdc2
	s_nop 0
	v_addc_co_u32_e32 v51, vcc, 0, v51, vcc
	v_add_co_u32_e32 v46, vcc, 0x2000, v46
	s_waitcnt lgkmcnt(1)
	v_mfma_f32_32x32x16_bf16 v[0:15], v[52:55], v[126:129], v[0:15]
	v_addc_co_u32_e32 v47, vcc, 0, v47, vcc
	ds_read_b128 v[52:55], v191 offset:16512
	ds_read_b128 v[64:67], v191 offset:16544
	global_load_dwordx4 v[138:141], v[56:57], off offset:128
	global_load_dwordx4 v[142:145], v[50:51], off
	global_load_dwordx4 v[146:149], v[46:47], off
	s_waitcnt lgkmcnt(1)
	v_mfma_f32_32x32x16_bf16 v[16:31], v[52:55], v[118:121], v[16:31]
	ds_read_b128 v[50:53], v191 offset:23168
	ds_read_b128 v[54:57], v191 offset:23200
	s_waitcnt vmcnt(3)
	ds_write_b128 v192, v[36:39] offset:8192
	ds_write_b128 v193, v[40:43] offset:29696
	v_add_u32_e32 v36, v48, v49
	v_mfma_f32_32x32x16_bf16 v[0:15], v[60:63], v[122:125], v[0:15]
	s_waitcnt lgkmcnt(4)
	v_mfma_f32_32x32x16_bf16 v[16:31], v[64:67], v[114:117], v[16:31]
	s_waitcnt lgkmcnt(3)
	v_mfma_f32_32x32x16_bf16 v[0:15], v[50:53], v[118:121], v[0:15]
	s_nop 9
	v_max_f32_e32 v46, v17, v17
	v_max_f32_e32 v47, v16, v16
	v_max_f32_e32 v46, v47, v46
	v_max3_f32 v46, v46, v18, v19
	v_max3_f32 v46, v46, v20, v21
	v_max3_f32 v46, v46, v22, v23
	v_max3_f32 v46, v46, v24, v25
	s_waitcnt lgkmcnt(2)
; #define SLOAD(i, k0) do { st_[i].vs = *reinterpret_cast<const bf16x8*>(&Vh[(size_t)((k0) + sr) * LDK + sc]); \
;     st_[i].ks = *reinterpret_cast<const bf16x8*>(&Kh[(size_t)((k0) + sr) * LDK + sc]); \
;     if (DQ == 96) st_[i].kr = *reinterpret_cast<const bf16x8*>(&Kr[(size_t)((k0) + sr2) * 32 + sc2]); } while (0)
; #define SWRITE(b, i) do { *(bf16x8*)(V_lds + (b) * SHM_V + vst0) = st_[i].vs; *(bf16x8*)(K_lds + (b) * SHM_K + kst0) = st_[i].ks; \
;     if (DQ == 96) { if (tid < 256) *(bf16x8*)(K_lds + (b) * SHM_K + kst2) = st_[i].kr; } } while (0)
; #define SWAIT() do { if (DQ == 96) asm volatile("s_waitcnt vmcnt(3)" ::: "memory"); else asm volatile("s_waitcnt vmcnt(2)" ::: "memory"); } while (0)
; #define SLOAD(i, k0) do { st_[i].vs = *reinterpret_cast<const bf16x8*>(&Vh[(size_t)((k0) + sr) * LDK + sc]); \
;     st_[i].ks = *reinterpret_cast<const bf16x8*>(&Kh[(size_t)((k0) + sr) * LDK + sc]); \
;     if (DQ == 96) st_[i].kr = *reinterpret_cast<const bf16x8*>(&Kr[(size_t)((k0) + sr2) * 32 + sc2]); } while (0)
; #define SWRITE(b, i) do { *(bf16x8*)(V_lds + (b) * SHM_V + vst0) = st_[i].vs; *(bf16x8*)(K_lds + (b) * SHM_K + kst0) = st_[i].ks; \
;     if (DQ == 96) { if (tid < 256) *(bf16x8*)(K_lds + (b) * SHM_K + kst2) = st_[i].kr; } } while (0)
; #define SWAIT() do { if (DQ == 96) asm volatile("s_waitcnt vmcnt(3)" ::: "memory"); else asm volatile("s_waitcnt vmcnt(2)" ::: "memory"); } while (0)
; template <int DQ, bool WIN, int LDQ, int LDK> ...
;     ...
;     qkt<DQ>(pA0, pA1, K_lds, qr, zero16, r32, hi);
;     if (WIN) win_mask(pA0, pA1, qrow - KBASE(0), hi);
;     { const float pm = row_max32(pA0, pA1); m_ref = (pm > -1e37f) ? pm : 0.f;
; #pragma unroll
;       for (int r = 0; r < 16; ++r) { minit[r] = -m_ref; pA0[r] -= m_ref; pA1[r] -= m_ref; } }
;     exp16(pA0);
;     if (2 < NT) SLOAD(SE, KBASE(2));
;     SWAIT(); SWRITE(1, SO); __syncthreads();
	v_mfma_f32_32x32x16_bf16 v[0:15], v[54:57], v[114:117], v[0:15]
	v_max3_f32 v46, v46, v26, v27
	v_max3_f32 v46, v46, v28, v29
	v_max3_f32 v46, v46, v30, v31
	s_nop 8
	v_max3_f32 v46, v46, v0, v1
	v_max3_f32 v46, v46, v2, v3
	v_max3_f32 v46, v46, v4, v5
	v_max3_f32 v46, v46, v6, v7
	v_max3_f32 v46, v46, v8, v9
	v_max3_f32 v46, v46, v10, v11
	v_max3_f32 v46, v46, v12, v13
	v_max3_f32 v46, v46, v14, v15
	v_mov_b32_e32 v47, v46
	s_nop 1
	v_permlane32_swap_b32_e32 v46, v47
	v_max_f32_e32 v47, v47, v47
	v_max_f32_e32 v46, v46, v46
	v_max_f32_e32 v46, v46, v47
	v_cmp_lt_f32_e32 vcc, s16, v46
	s_and_saveexec_b64 s[16:17], s[4:5]
	s_xor_b64 s[4:5], exec, s[16:17]
	v_add_u32_e32 v36, v48, v49
	s_andn2_saveexec_b64 s[4:5], s[4:5]
	v_add_u32_e32 v37, 0, v36
	ds_write_b128 v37, v[32:35] offset:29824
	s_or_b64 exec, exec, s[4:5]
	v_and_b32_e32 v189, 63, v80
	v_cndmask_b32_e32 v32, 0, v46, vcc
	v_sub_f32_e32 v65, v1, v32
	v_lshlrev_b32_e32 v1, 4, v189
	s_lshr_b32 s4, s20, 5
	s_and_b32 s16, s18, 0xffffffe0
	v_sub_f32_e32 v66, v2, v32
	v_sub_f32_e32 v64, v0, v32
	v_lshlrev_b32_e32 v0, 3, v189
	v_and_b32_e32 v1, 0xc0, v1
	v_lshlrev_b32_e32 v2, 1, v189
	v_and_or_b32 v1, v0, 24, v1
	v_and_b32_e32 v2, 32, v2
	v_and_b32_e32 v0, 0x100, v0
	s_cmp_lg_u32 0, -1
	v_or3_b32 v0, v1, v2, v0
	s_cselect_b32 s5, 0, 0
	s_and_b32 s4, s4, 15
	v_add_u32_e32 v194, s5, v0
	s_lshl_b32 s21, s4, 8
	s_addk_i32 s5, 0x2000
	s_add_u32 s10, s10, 0x10800000
	s_addc_u32 s11, s11, 0
	v_sub_f32_e32 v16, v16, v32
	v_sub_f32_e32 v17, v17, v32
	v_sub_f32_e32 v18, v18, v32
	v_sub_f32_e32 v19, v19, v32
	v_sub_f32_e32 v20, v20, v32
	v_sub_f32_e32 v21, v21, v32
	v_sub_f32_e32 v22, v22, v32
	v_sub_f32_e32 v23, v23, v32
	v_sub_f32_e32 v24, v24, v32
	v_sub_f32_e32 v25, v25, v32
	v_sub_f32_e32 v26, v26, v32
	v_sub_f32_e32 v27, v27, v32
	v_sub_f32_e32 v28, v28, v32
	v_sub_f32_e32 v29, v29, v32
	v_sub_f32_e32 v30, v30, v32
	v_sub_f32_e32 v31, v31, v32
	v_add_lshl_u32 v2, v82, v81, 1
	s_add_u32 s4, s21, s0
	v_exp_f32_e32 v161, v16
	v_exp_f32_e32 v196, v17
	v_exp_f32_e32 v158, v18
	v_exp_f32_e32 v168, v19
	v_exp_f32_e32 v159, v20
	v_exp_f32_e32 v169, v21
	v_exp_f32_e32 v160, v22
	v_exp_f32_e32 v195, v23
	v_exp_f32_e32 v150, v24
	v_exp_f32_e32 v154, v25
	v_exp_f32_e32 v151, v26
	v_exp_f32_e32 v155, v27
	v_exp_f32_e32 v152, v28
	v_exp_f32_e32 v156, v29
	v_exp_f32_e32 v153, v30
	v_exp_f32_e32 v157, v31
	v_sub_f32_e32 v67, v3, v32
	v_add_u32_e32 v190, s5, v0
	v_or_b32_e32 v112, 0x4000, v2
	s_addc_u32 s5, 0, s1
	v_and_b32_e32 v3, 7, v80
	v_lshl_add_u64 v[162:163], s[10:11], 0, v[112:113]
	v_lshl_add_u64 v[0:1], s[4:5], 0, v[44:45]
	v_lshlrev_b32_e32 v112, 4, v3
	v_xor_b32_e32 v48, 0x80000000, v32
	v_lshl_add_u64 v[164:165], v[0:1], 0, v[112:113]
	v_add_u32_e32 v112, 0x3000, v2
	v_mov_b32_e32 v0, 0
	v_mov_b32_e32 v49, v48
	v_mov_b32_e32 v50, v48
	v_mov_b32_e32 v51, v48
	v_mov_b32_e32 v52, v48
	v_mov_b32_e32 v53, v48
	v_mov_b32_e32 v54, v48
	v_mov_b32_e32 v55, v48
	v_mov_b32_e32 v56, v48
	v_mov_b32_e32 v57, v48
	v_mov_b32_e32 v58, v48
	v_mov_b32_e32 v59, v48
	v_mov_b32_e32 v60, v48
	v_mov_b32_e32 v61, v48
	v_mov_b32_e32 v62, v48
	v_mov_b32_e32 v63, v48
	v_sub_f32_e32 v79, v15, v32
	v_sub_f32_e32 v78, v14, v32
	v_sub_f32_e32 v77, v13, v32
	v_sub_f32_e32 v76, v12, v32
	v_sub_f32_e32 v75, v11, v32
	v_sub_f32_e32 v74, v10, v32
	v_sub_f32_e32 v73, v9, v32
	v_sub_f32_e32 v72, v8, v32
	v_sub_f32_e32 v71, v7, v32
	v_sub_f32_e32 v70, v6, v32
	v_sub_f32_e32 v69, v5, v32
	v_sub_f32_e32 v68, v4, v32
	s_mov_b32 s17, -1
	v_lshl_add_u64 v[166:167], s[10:11], 0, v[112:113]
	v_add_u32_e32 v112, 0, v36
	v_mov_b32_e32 v1, v0
	v_mov_b32_e32 v2, v0
	v_mov_b32_e32 v3, v0
	v_mov_b32_e32 v4, v0
	v_mov_b32_e32 v5, v0
	v_mov_b32_e32 v6, v0
	v_mov_b32_e32 v7, v0
	v_mov_b32_e32 v8, v0
	v_mov_b32_e32 v9, v0
	v_mov_b32_e32 v10, v0
	v_mov_b32_e32 v11, v0
	v_mov_b32_e32 v12, v0
	v_mov_b32_e32 v13, v0
	v_mov_b32_e32 v14, v0
	v_mov_b32_e32 v15, v0
	v_mov_b32_e32 v16, v0
	v_mov_b32_e32 v17, v0
	v_mov_b32_e32 v18, v0
	v_mov_b32_e32 v19, v0
	v_mov_b32_e32 v20, v0
	v_mov_b32_e32 v21, v0
	v_mov_b32_e32 v22, v0
	v_mov_b32_e32 v23, v0
	v_mov_b32_e32 v24, v0
	v_mov_b32_e32 v25, v0
	v_mov_b32_e32 v26, v0
	v_mov_b32_e32 v27, v0
	v_mov_b32_e32 v28, v0
	v_mov_b32_e32 v29, v0
	v_mov_b32_e32 v30, v0
	v_mov_b32_e32 v31, v0
	v_mov_b32_e32 v32, v0
	v_mov_b32_e32 v33, v0
	v_mov_b32_e32 v34, v0
	v_mov_b32_e32 v35, v0
	v_lshrrev_b32_e32 v36, 4, v189
	v_xor_b32_e32 v36, v36, v189
	v_not_b32_e32 v36, v36
	v_bfe_i32 v36, v36, 0, 1
	v_and_b32_e32 v36, 0x3f803f80, v36
	v_mov_b32_e32 v37, v36
	v_mov_b32_e32 v38, v36
	v_mov_b32_e32 v39, v36
	v_mov_b32_e32 v40, v0
	v_mov_b32_e32 v41, v0
	v_mov_b32_e32 v42, v0
	v_mov_b32_e32 v43, v0
	v_mov_b32_e32 v44, v0
	v_mov_b32_e32 v45, v0
	v_mov_b32_e32 v46, v0
	v_mov_b32_e32 v47, v0
	v_xor_b32_e32 v192, 0xc000, v192
	v_lshl_add_u64 v[162:163], v[162:163], 0, s[26:27]
	v_lshl_add_u64 v[166:167], v[166:167], 0, s[26:27]
	v_lshl_add_u64 v[164:165], v[164:165], 0, s[26:27]
	v_add_co_u32_e32 v164, vcc, 0x218c0000, v164
	s_nop 1
	v_addc_co_u32_e32 v165, vcc, 0, v165, vcc
	s_mov_b64 s[34:35], 0x2000
	s_mov_b64 s[18:19], 0x80000
	s_waitcnt lgkmcnt(0)
	s_barrier
	s_branch .LBB0_1094

; #define SBAR() __builtin_amdgcn_sched_barrier(0)
; #define SLOAD(i, k0) do { st_[i].vs = *reinterpret_cast<const bf16x8*>(&Vh[(size_t)((k0) + sr) * LDK + sc]); \
;     st_[i].ks = *reinterpret_cast<const bf16x8*>(&Kh[(size_t)((k0) + sr) * LDK + sc]); \
;     if (DQ == 96) st_[i].kr = *reinterpret_cast<const bf16x8*>(&Kr[(size_t)((k0) + sr2) * 32 + sc2]); } while (0)
; #define SWRITE(b, i) do { *(bf16x8*)(V_lds + (b) * SHM_V + vst0) = st_[i].vs; *(bf16x8*)(K_lds + (b) * SHM_K + kst0) = st_[i].ks; \
;     if (DQ == 96) { if (tid < 256) *(bf16x8*)(K_lds + (b) * SHM_K + kst2) = st_[i].kr; } } while (0)
; #define SWAIT() do { if (DQ == 96) asm volatile("s_waitcnt vmcnt(3)" ::: "memory"); else asm volatile("s_waitcnt vmcnt(2)" ::: "memory"); } while (0)
; #define SLOAD(i, k0) do { st_[i].vs = *reinterpret_cast<const bf16x8*>(&Vh[(size_t)((k0) + sr) * LDK + sc]); \
;     st_[i].ks = *reinterpret_cast<const bf16x8*>(&Kh[(size_t)((k0) + sr) * LDK + sc]); \
;     if (DQ == 96) st_[i].kr = *reinterpret_cast<const bf16x8*>(&Kr[(size_t)((k0) + sr2) * 32 + sc2]); } while (0)
; #define SWRITE(b, i) do { *(bf16x8*)(V_lds + (b) * SHM_V + vst0) = st_[i].vs; *(bf16x8*)(K_lds + (b) * SHM_K + kst0) = st_[i].ks; \
;     if (DQ == 96) { if (tid < 256) *(bf16x8*)(K_lds + (b) * SHM_K + kst2) = st_[i].kr; } } while (0)
; #define SWAIT() do { if (DQ == 96) asm volatile("s_waitcnt vmcnt(3)" ::: "memory"); else asm volatile("s_waitcnt vmcnt(2)" ::: "memory"); } while (0)
; template <int DQ, bool WIN, int LDQ, int LDK> ...
;     ...
;         SBAR(); qkt<DQ>(pB0, pB1, K_lds + SHM_K, qr, minit, r32, hi);
;         finish(pA0, pA1); SBAR();
;         SLOAD(SO, KBASE(j + 2)); SBAR();
;         pv(vb0);
;         __syncthreads(); SWAIT(); SWRITE(0, SE);
;         lsum_upd();
.LBB0_1094:
	ds_read_b64_tr_b16 v[40:41], v194 offset:0
	ds_read_b64_tr_b16 v[42:43], v194 offset:0x400
	ds_read_b64_tr_b16 v[44:45], v194 offset:0x800
	ds_read_b64_tr_b16 v[46:47], v194 offset:0xc00
	ds_read_b128 v[198:201], v191 offset:36352
	ds_read_b128 v[80:83], v191 offset:29696
	ds_read_b128 v[202:205], v191 offset:29728
	v_exp_f32_e32 v72, v72
	v_exp_f32_e32 v73, v73
	v_exp_f32_e32 v74, v74
	s_waitcnt lgkmcnt(1)
	v_mfma_f32_32x32x16_bf16 v[96:111], v[80:83], v[134:137], v[48:63]
	v_exp_f32_e32 v75, v75
	v_exp_f32_e32 v197, v64
	v_exp_f32_e32 v206, v77
	v_exp_f32_e32 v207, v78
	v_exp_f32_e32 v208, v79
	v_mfma_f32_32x32x16_bf16 v[80:95], v[198:201], v[134:137], v[48:63]
	ds_read_b128 v[198:201], v191 offset:36384
	s_waitcnt lgkmcnt(1)
	v_mfma_f32_32x32x16_bf16 v[96:111], v[202:205], v[130:133], v[96:111]
	s_waitcnt lgkmcnt(0)
	v_mfma_f32_32x32x16_bf16 v[80:95], v[198:201], v[130:133], v[80:95]
	ds_read_b128 v[198:201], v191 offset:29760
	ds_read_b128 v[202:205], v191 offset:36416
	s_waitcnt lgkmcnt(1)
	v_mfma_f32_32x32x16_bf16 v[96:111], v[198:201], v[126:129], v[96:111]
	s_waitcnt lgkmcnt(0)
	v_mfma_f32_32x32x16_bf16 v[80:95], v[202:205], v[126:129], v[80:95]
	ds_read_b128 v[198:201], v191 offset:29792
	ds_read_b128 v[202:205], v191 offset:36448
	s_waitcnt lgkmcnt(1)
	v_mfma_f32_32x32x16_bf16 v[96:111], v[198:201], v[122:125], v[96:111]
	s_waitcnt lgkmcnt(0)
	v_mfma_f32_32x32x16_bf16 v[80:95], v[202:205], v[122:125], v[80:95]
	ds_read_b128 v[198:201], v191 offset:29824
	ds_read_b128 v[202:205], v191 offset:36480
	s_waitcnt lgkmcnt(1)
	v_mfma_f32_32x32x16_bf16 v[96:111], v[198:201], v[118:121], v[96:111]
	s_waitcnt lgkmcnt(0)
	v_mfma_f32_32x32x16_bf16 v[80:95], v[202:205], v[118:121], v[80:95]
	ds_read_b128 v[198:201], v191 offset:29856
	ds_read_b128 v[202:205], v191 offset:36512
	s_waitcnt lgkmcnt(1)
	v_mfma_f32_32x32x16_bf16 v[96:111], v[198:201], v[114:117], v[96:111]
	v_exp_f32_e32 v198, v65
	v_exp_f32_e32 v199, v66
	v_exp_f32_e32 v200, v67
	v_exp_f32_e32 v201, v68
	v_cvt_pk_bf16_f32 v68, v161, v196
	s_waitcnt lgkmcnt(0)
	v_mfma_f32_32x32x16_bf16 v[80:95], v[202:205], v[114:117], v[80:95]
	v_exp_f32_e32 v202, v69
	v_exp_f32_e32 v203, v70
	v_exp_f32_e32 v204, v71
	v_exp_f32_e32 v205, v76
	v_cvt_pk_bf16_f32 v69, v158, v168
	v_cvt_pk_bf16_f32 v70, v159, v169
	v_cvt_pk_bf16_f32 v71, v160, v195
	v_cvt_pk_bf16_f32 v64, v150, v154
	v_cvt_pk_bf16_f32 v65, v151, v155
	v_cvt_pk_bf16_f32 v66, v152, v156
	v_cvt_pk_bf16_f32 v67, v153, v157
	v_cvt_pk_bf16_f32 v76, v197, v198
	v_cvt_pk_bf16_f32 v77, v199, v200
	v_cvt_pk_bf16_f32 v78, v201, v202
	v_cvt_pk_bf16_f32 v79, v203, v204
	v_cvt_pk_bf16_f32 v72, v72, v73
	v_cvt_pk_bf16_f32 v73, v74, v75
	v_cvt_pk_bf16_f32 v74, v205, v206
	v_cvt_pk_bf16_f32 v75, v207, v208
	global_load_dwordx4 v[154:157], v[164:165], off offset:128
	global_load_dwordx4 v[158:161], v[164:165], off
	global_load_dwordx4 v[150:153], v[166:167], off
	ds_read_b64_tr_b16 v[204:205], v194 offset:0x1000
	ds_read_b64_tr_b16 v[206:207], v194 offset:0x1400
	ds_read_b64_tr_b16 v[208:209], v194 offset:0x1800
	ds_read_b64_tr_b16 v[210:211], v194 offset:0x1c00
	ds_read_b64_tr_b16 v[196:197], v194 offset:0x200
	ds_read_b64_tr_b16 v[198:199], v194 offset:0x600
	ds_read_b64_tr_b16 v[200:201], v194 offset:0xa00
	ds_read_b64_tr_b16 v[202:203], v194 offset:0xe00
	v_mfma_f32_32x32x16_bf16 v[0:15], v[68:71], v[40:43], v[0:15]
	v_mfma_f32_32x32x16_bf16 v[0:15], v[64:67], v[44:47], v[0:15]
	s_waitcnt lgkmcnt(6)
	v_mfma_f32_32x32x16_bf16 v[0:15], v[76:79], v[204:207], v[0:15]
	ds_read_b64_tr_b16 v[204:205], v194 offset:0x1200
	ds_read_b64_tr_b16 v[206:207], v194 offset:0x1600
	s_waitcnt lgkmcnt(6)
	v_mfma_f32_32x32x16_bf16 v[0:15], v[72:75], v[208:211], v[0:15]
	ds_read_b64_tr_b16 v[208:209], v194 offset:0x1a00
	ds_read_b64_tr_b16 v[210:211], v194 offset:0x1e00
	s_waitcnt lgkmcnt(0)
	v_mfma_f32_32x32x16_bf16 v[16:31], v[68:71], v[196:199], v[16:31]
	s_waitcnt vmcnt(3)
	ds_write_b128 v192, v[138:141]
	ds_write_b128 v193, v[142:145] offset:16384
	v_mfma_f32_32x32x16_bf16 v[16:31], v[64:67], v[200:203], v[16:31]
	v_mfma_f32_32x32x16_bf16 v[16:31], v[76:79], v[204:207], v[16:31]
	v_mfma_f32_32x32x16_bf16 v[16:31], v[72:75], v[208:211], v[16:31]
	ds_write_b128 v112, v[146:149] offset:16512
; #define SBAR() __builtin_amdgcn_sched_barrier(0)
; #define SLOAD(i, k0) do { st_[i].vs = *reinterpret_cast<const bf16x8*>(&Vh[(size_t)((k0) + sr) * LDK + sc]); \
;     st_[i].ks = *reinterpret_cast<const bf16x8*>(&Kh[(size_t)((k0) + sr) * LDK + sc]); \
;     if (DQ == 96) st_[i].kr = *reinterpret_cast<const bf16x8*>(&Kr[(size_t)((k0) + sr2) * 32 + sc2]); } while (0)
; #define SWRITE(b, i) do { *(bf16x8*)(V_lds + (b) * SHM_V + vst0) = st_[i].vs; *(bf16x8*)(K_lds + (b) * SHM_K + kst0) = st_[i].ks; \
;     if (DQ == 96) { if (tid < 256) *(bf16x8*)(K_lds + (b) * SHM_K + kst2) = st_[i].kr; } } while (0)
; #define SWAIT() do { if (DQ == 96) asm volatile("s_waitcnt vmcnt(3)" ::: "memory"); else asm volatile("s_waitcnt vmcnt(2)" ::: "memory"); } while (0)
; #define SLOAD(i, k0) do { st_[i].vs = *reinterpret_cast<const bf16x8*>(&Vh[(size_t)((k0) + sr) * LDK + sc]); \
;     st_[i].ks = *reinterpret_cast<const bf16x8*>(&Kh[(size_t)((k0) + sr) * LDK + sc]); \
;     if (DQ == 96) st_[i].kr = *reinterpret_cast<const bf16x8*>(&Kr[(size_t)((k0) + sr2) * 32 + sc2]); } while (0)
; #define SWRITE(b, i) do { *(bf16x8*)(V_lds + (b) * SHM_V + vst0) = st_[i].vs; *(bf16x8*)(K_lds + (b) * SHM_K + kst0) = st_[i].ks; \
;     if (DQ == 96) { if (tid < 256) *(bf16x8*)(K_lds + (b) * SHM_K + kst2) = st_[i].kr; } } while (0)
; #define SWAIT() do { if (DQ == 96) asm volatile("s_waitcnt vmcnt(3)" ::: "memory"); else asm volatile("s_waitcnt vmcnt(2)" ::: "memory"); } while (0)
; template <int DQ, bool WIN, int LDQ, int LDK> ...
;     ...
;         SBAR(); qkt<DQ>(pA0, pA1, K_lds, qr, minit, r32, hi);
;         finish(pB0, pB1); SBAR();
;         if (j + 3 < NT) SLOAD(SE, KBASE(j + 3)); SBAR();
;         pv(vb0 + SHM_V);
;         __syncthreads(); SWAIT(); SWRITE(1, SO);
;         lsum_upd();
;         if (WIN) win_mask(pA0, pA1, qrow - KBASE(j + 1), hi);
;         exp16(pA0);
.LBB0_1096:
	s_add_i32 s17, s17, 2
	v_exp_f32_e32 v195, v96
	v_mfma_f32_16x16x32_bf16 v[32:35], v[68:71], v[36:39], v[32:35]
	v_exp_f32_e32 v204, v97
	v_exp_f32_e32 v205, v98
	v_exp_f32_e32 v206, v99
	v_exp_f32_e32 v207, v100
	v_exp_f32_e32 v208, v101
	v_exp_f32_e32 v209, v102
	v_exp_f32_e32 v210, v103
	v_mfma_f32_16x16x32_bf16 v[32:35], v[64:67], v[36:39], v[32:35]
	v_exp_f32_e32 v211, v104
	v_exp_f32_e32 v212, v105
	v_exp_f32_e32 v213, v106
	v_exp_f32_e32 v214, v107
	v_exp_f32_e32 v215, v108
	v_exp_f32_e32 v216, v109
	v_exp_f32_e32 v217, v110
	v_mfma_f32_16x16x32_bf16 v[32:35], v[76:79], v[36:39], v[32:35]
	v_exp_f32_e32 v218, v111
	s_waitcnt lgkmcnt(0)
	s_barrier
	v_mfma_f32_16x16x32_bf16 v[32:35], v[72:75], v[36:39], v[32:35]
	ds_read_b64_tr_b16 v[40:41], v190 offset:0
	ds_read_b64_tr_b16 v[42:43], v190 offset:0x400
	ds_read_b64_tr_b16 v[44:45], v190 offset:0x800
	ds_read_b64_tr_b16 v[46:47], v190 offset:0xc00
	ds_read_b128 v[196:199], v191 offset:23040
	ds_read_b128 v[64:67], v191 offset:16384
	ds_read_b128 v[200:203], v191 offset:16416
	v_exp_f32_e32 v95, v95
	v_exp_f32_e32 v219, v88
	v_exp_f32_e32 v220, v89
	s_waitcnt lgkmcnt(1)
	v_mfma_f32_32x32x16_bf16 v[96:111], v[64:67], v[134:137], v[48:63]
	v_exp_f32_e32 v221, v90
	v_exp_f32_e32 v222, v91
	v_exp_f32_e32 v223, v92
	v_exp_f32_e32 v224, v93
	v_exp_f32_e32 v225, v94
	v_mfma_f32_32x32x16_bf16 v[64:79], v[196:199], v[134:137], v[48:63]
	ds_read_b128 v[196:199], v191 offset:23072
	s_waitcnt lgkmcnt(1)
	v_mfma_f32_32x32x16_bf16 v[96:111], v[200:203], v[130:133], v[96:111]
	s_waitcnt lgkmcnt(0)
	v_mfma_f32_32x32x16_bf16 v[64:79], v[196:199], v[130:133], v[64:79]
	ds_read_b128 v[196:199], v191 offset:16448
	ds_read_b128 v[200:203], v191 offset:23104
	s_waitcnt lgkmcnt(1)
	v_mfma_f32_32x32x16_bf16 v[96:111], v[196:199], v[126:129], v[96:111]
	s_waitcnt lgkmcnt(0)
	v_mfma_f32_32x32x16_bf16 v[64:79], v[200:203], v[126:129], v[64:79]
	ds_read_b128 v[196:199], v191 offset:16480
	ds_read_b128 v[200:203], v191 offset:23136
	s_waitcnt lgkmcnt(1)
	v_mfma_f32_32x32x16_bf16 v[96:111], v[196:199], v[122:125], v[96:111]
	s_waitcnt lgkmcnt(0)
	v_mfma_f32_32x32x16_bf16 v[64:79], v[200:203], v[122:125], v[64:79]
	ds_read_b128 v[196:199], v191 offset:16512
	ds_read_b128 v[200:203], v191 offset:23168
	s_waitcnt lgkmcnt(1)
	v_mfma_f32_32x32x16_bf16 v[96:111], v[196:199], v[118:121], v[96:111]
	s_waitcnt lgkmcnt(0)
	v_mfma_f32_32x32x16_bf16 v[64:79], v[200:203], v[118:121], v[64:79]
	ds_read_b128 v[196:199], v191 offset:16544
	ds_read_b128 v[200:203], v191 offset:23200
	s_waitcnt lgkmcnt(1)
	v_mfma_f32_32x32x16_bf16 v[96:111], v[196:199], v[114:117], v[96:111]
	v_exp_f32_e32 v196, v80
	v_exp_f32_e32 v197, v81
	v_exp_f32_e32 v198, v82
	v_exp_f32_e32 v199, v83
	v_cvt_pk_bf16_f32 v80, v195, v204
	v_cvt_pk_bf16_f32 v81, v205, v206
	v_cvt_pk_bf16_f32 v82, v207, v208
	s_waitcnt lgkmcnt(0)
	v_mfma_f32_32x32x16_bf16 v[64:79], v[200:203], v[114:117], v[64:79]
	v_exp_f32_e32 v200, v84
	v_exp_f32_e32 v201, v85
	v_exp_f32_e32 v202, v86
	v_exp_f32_e32 v203, v87
	v_cvt_pk_bf16_f32 v83, v209, v210
	v_cvt_pk_bf16_f32 v84, v211, v212
	v_cvt_pk_bf16_f32 v85, v213, v214
	v_cvt_pk_bf16_f32 v86, v215, v216
	v_cvt_pk_bf16_f32 v87, v217, v218
	v_cvt_pk_bf16_f32 v88, v196, v197
	v_cvt_pk_bf16_f32 v89, v198, v199
	v_cvt_pk_bf16_f32 v90, v200, v201
	v_cvt_pk_bf16_f32 v91, v202, v203
	v_cvt_pk_bf16_f32 v92, v219, v220
	v_cvt_pk_bf16_f32 v93, v221, v222
	v_cvt_pk_bf16_f32 v94, v223, v224
	v_cvt_pk_bf16_f32 v95, v225, v95
	v_add_co_u32_e32 v142, vcc, 0x40000, v164
	s_nop 1
	v_addc_co_u32_e32 v143, vcc, 0, v165, vcc
	global_load_dwordx4 v[138:141], v[142:143], off offset:128
	global_load_dwordx4 v[142:145], v[142:143], off
	global_load_dwordx4 v[146:149], v[162:163], off
